# phase 0: ada matmul k-loop with 32 loads in flight, folded pool weight loop two trips per wait
# speedup vs baseline: 1.0089x; 1.0006x over previous
; DEVI void ph_setup(const int wv, const Params& p, unsigned char* lds) {
;     ...
;             const float* w = p.in[6] + (size_t)l * 1024 * 6144 + n0 + n;
;             for (int k = kg * 128; k < kg * 128 + 128; ++k) { const float wv = w[(size_t)k * 6144];
; #pragma unroll
;                 for (int r = 0; r < 17; ++r) acc[r] += scv[r * 1024 + k] * wv; }
.LBB0_45:
	global_load_dword v100, v[8:9], off
	v_add_co_u32_e32 v38, vcc, s48, v8
	s_nop 1
	v_addc_co_u32_e32 v39, vcc, 0, v9, vcc
	global_load_dword v102, v[38:39], off
	v_lshl_add_u64 v[8:9], v[8:9], 0, s[38:39]
	global_load_dword v104, v[8:9], off
	v_add_co_u32_e32 v38, vcc, s48, v8
	s_nop 1
	v_addc_co_u32_e32 v39, vcc, 0, v9, vcc
	global_load_dword v106, v[38:39], off
	v_lshl_add_u64 v[8:9], v[8:9], 0, s[38:39]
	global_load_dword v108, v[8:9], off
	v_add_co_u32_e32 v38, vcc, s48, v8
	s_nop 1
	v_addc_co_u32_e32 v39, vcc, 0, v9, vcc
	global_load_dword v110, v[38:39], off
	v_lshl_add_u64 v[8:9], v[8:9], 0, s[38:39]
	global_load_dword v112, v[8:9], off
	v_add_co_u32_e32 v38, vcc, s48, v8
	s_nop 1
	v_addc_co_u32_e32 v39, vcc, 0, v9, vcc
	global_load_dword v114, v[38:39], off
	v_lshl_add_u64 v[8:9], v[8:9], 0, s[38:39]
	global_load_dword v116, v[8:9], off
	v_add_co_u32_e32 v38, vcc, s48, v8
	s_nop 1
	v_addc_co_u32_e32 v39, vcc, 0, v9, vcc
	global_load_dword v118, v[38:39], off
	v_lshl_add_u64 v[8:9], v[8:9], 0, s[38:39]
	global_load_dword v120, v[8:9], off
	v_add_co_u32_e32 v38, vcc, s48, v8
	s_nop 1
	v_addc_co_u32_e32 v39, vcc, 0, v9, vcc
	global_load_dword v122, v[38:39], off
	v_lshl_add_u64 v[8:9], v[8:9], 0, s[38:39]
	global_load_dword v124, v[8:9], off
	v_add_co_u32_e32 v38, vcc, s48, v8
	s_nop 1
	v_addc_co_u32_e32 v39, vcc, 0, v9, vcc
	global_load_dword v126, v[38:39], off
	v_lshl_add_u64 v[8:9], v[8:9], 0, s[38:39]
	global_load_dword v128, v[8:9], off
	v_add_co_u32_e32 v38, vcc, s48, v8
	s_nop 1
	v_addc_co_u32_e32 v39, vcc, 0, v9, vcc
	global_load_dword v130, v[38:39], off
	v_lshl_add_u64 v[8:9], v[8:9], 0, s[38:39]
	global_load_dword v132, v[8:9], off
	v_add_co_u32_e32 v38, vcc, s48, v8
	s_nop 1
	v_addc_co_u32_e32 v39, vcc, 0, v9, vcc
	global_load_dword v134, v[38:39], off
	v_lshl_add_u64 v[8:9], v[8:9], 0, s[38:39]
	global_load_dword v136, v[8:9], off
	v_add_co_u32_e32 v38, vcc, s48, v8
	s_nop 1
	v_addc_co_u32_e32 v39, vcc, 0, v9, vcc
	global_load_dword v138, v[38:39], off
	v_lshl_add_u64 v[8:9], v[8:9], 0, s[38:39]
	global_load_dword v140, v[8:9], off
	v_add_co_u32_e32 v38, vcc, s48, v8
	s_nop 1
	v_addc_co_u32_e32 v39, vcc, 0, v9, vcc
	global_load_dword v142, v[38:39], off
	v_lshl_add_u64 v[8:9], v[8:9], 0, s[38:39]
	global_load_dword v144, v[8:9], off
	v_add_co_u32_e32 v38, vcc, s48, v8
	s_nop 1
	v_addc_co_u32_e32 v39, vcc, 0, v9, vcc
	global_load_dword v146, v[38:39], off
	v_lshl_add_u64 v[8:9], v[8:9], 0, s[38:39]
	global_load_dword v148, v[8:9], off
	v_add_co_u32_e32 v38, vcc, s48, v8
	s_nop 1
	v_addc_co_u32_e32 v39, vcc, 0, v9, vcc
	global_load_dword v150, v[38:39], off
	v_lshl_add_u64 v[8:9], v[8:9], 0, s[38:39]
	global_load_dword v152, v[8:9], off
	v_add_co_u32_e32 v38, vcc, s48, v8
	s_nop 1
	v_addc_co_u32_e32 v39, vcc, 0, v9, vcc
	global_load_dword v154, v[38:39], off
	v_lshl_add_u64 v[8:9], v[8:9], 0, s[38:39]
	global_load_dword v156, v[8:9], off
	v_add_co_u32_e32 v38, vcc, s48, v8
	s_nop 1
	v_addc_co_u32_e32 v39, vcc, 0, v9, vcc
	global_load_dword v158, v[38:39], off
	v_lshl_add_u64 v[8:9], v[8:9], 0, s[38:39]
	global_load_dword v160, v[8:9], off
	v_add_co_u32_e32 v38, vcc, s48, v8
	s_nop 1
	v_addc_co_u32_e32 v39, vcc, 0, v9, vcc
	global_load_dword v162, v[38:39], off
	v_lshl_add_u64 v[8:9], v[8:9], 0, s[38:39]
	v_add_u32_e32 v37, s14, v35
	ds_read2st64_b64 v[38:41], v37 offset1:8
	ds_read2st64_b64 v[42:45], v37 offset0:16 offset1:24
	ds_read2st64_b64 v[46:49], v37 offset0:32 offset1:40
	ds_read2st64_b64 v[50:53], v37 offset0:48 offset1:56
	ds_read2st64_b64 v[54:57], v37 offset0:64 offset1:72
	ds_read2st64_b64 v[58:61], v37 offset0:80 offset1:88
	ds_read2st64_b64 v[62:65], v37 offset0:96 offset1:104
	ds_read2st64_b64 v[66:69], v37 offset0:112 offset1:120
	v_add_u32_e32 v37, 0x10000, v37
	ds_read_b64 v[74:75], v37
	s_waitcnt lgkmcnt(8)
	v_mov_b32_e32 v76, v38
	v_mov_b32_e32 v77, v40
	s_waitcnt lgkmcnt(7)
	v_mov_b32_e32 v78, v42
	v_mov_b32_e32 v79, v44
	s_waitcnt lgkmcnt(6)
	v_mov_b32_e32 v80, v46
	v_mov_b32_e32 v81, v48
	s_waitcnt lgkmcnt(5)
	v_mov_b32_e32 v82, v50
	v_mov_b32_e32 v83, v52
	s_waitcnt lgkmcnt(4)
	v_mov_b32_e32 v84, v54
	v_mov_b32_e32 v85, v56
	s_waitcnt lgkmcnt(3)
	v_mov_b32_e32 v86, v58
	v_mov_b32_e32 v87, v60
	s_waitcnt lgkmcnt(2)
	v_mov_b32_e32 v88, v62
	v_mov_b32_e32 v89, v64
	s_waitcnt lgkmcnt(1)
	v_mov_b32_e32 v90, v66
	v_mov_b32_e32 v91, v68
	s_add_i32 s14, s14, 8
	v_mov_b32_e32 v40, v39
	v_mov_b32_e32 v44, v43
	v_mov_b32_e32 v48, v47
	v_mov_b32_e32 v52, v51
	v_mov_b32_e32 v56, v55
	v_mov_b32_e32 v60, v59
	v_mov_b32_e32 v64, v63
	v_mov_b32_e32 v68, v67
	s_cmpk_eq_i32 s14, 0x200
	s_waitcnt vmcnt(31)
	v_pk_fma_f32 v[10:11], v[100:101], v[76:77], v[10:11] op_sel_hi:[0,1,1]
	v_pk_fma_f32 v[12:13], v[100:101], v[78:79], v[12:13] op_sel_hi:[0,1,1]
	v_pk_fma_f32 v[14:15], v[100:101], v[80:81], v[14:15] op_sel_hi:[0,1,1]
	v_pk_fma_f32 v[16:17], v[100:101], v[82:83], v[16:17] op_sel_hi:[0,1,1]
	v_pk_fma_f32 v[18:19], v[100:101], v[84:85], v[18:19] op_sel_hi:[0,1,1]
	v_pk_fma_f32 v[20:21], v[100:101], v[86:87], v[20:21] op_sel_hi:[0,1,1]
	v_pk_fma_f32 v[22:23], v[100:101], v[88:89], v[22:23] op_sel_hi:[0,1,1]
	v_pk_fma_f32 v[24:25], v[100:101], v[90:91], v[24:25] op_sel_hi:[0,1,1]
	s_waitcnt lgkmcnt(0)
	v_fmac_f32_e32 v2, v100, v74
	s_waitcnt vmcnt(30)
; DEVI void ph_setup(const int wv, const Params& p, unsigned char* lds) {
;     ...
;             const float* w = p.in[6] + (size_t)l * 1024 * 6144 + n0 + n;
;             for (int k = kg * 128; k < kg * 128 + 128; ++k) { const float wv = w[(size_t)k * 6144];
; #pragma unroll
;                 for (int r = 0; r < 17; ++r) acc[r] += scv[r * 1024 + k] * wv; }
	v_pk_fma_f32 v[10:11], v[102:103], v[40:41], v[10:11] op_sel_hi:[0,1,1]
	v_pk_fma_f32 v[12:13], v[102:103], v[44:45], v[12:13] op_sel_hi:[0,1,1]
	v_pk_fma_f32 v[14:15], v[102:103], v[48:49], v[14:15] op_sel_hi:[0,1,1]
	v_pk_fma_f32 v[16:17], v[102:103], v[52:53], v[16:17] op_sel_hi:[0,1,1]
	v_pk_fma_f32 v[18:19], v[102:103], v[56:57], v[18:19] op_sel_hi:[0,1,1]
	v_pk_fma_f32 v[20:21], v[102:103], v[60:61], v[20:21] op_sel_hi:[0,1,1]
	v_pk_fma_f32 v[22:23], v[102:103], v[64:65], v[22:23] op_sel_hi:[0,1,1]
	v_pk_fma_f32 v[24:25], v[102:103], v[68:69], v[24:25] op_sel_hi:[0,1,1]
	v_fmac_f32_e32 v2, v102, v75
	v_add_u32_e32 v37, s14, v35
	ds_read2st64_b64 v[38:41], v37 offset1:8
	ds_read2st64_b64 v[42:45], v37 offset0:16 offset1:24
	ds_read2st64_b64 v[46:49], v37 offset0:32 offset1:40
	ds_read2st64_b64 v[50:53], v37 offset0:48 offset1:56
	ds_read2st64_b64 v[54:57], v37 offset0:64 offset1:72
	ds_read2st64_b64 v[58:61], v37 offset0:80 offset1:88
	ds_read2st64_b64 v[62:65], v37 offset0:96 offset1:104
	ds_read2st64_b64 v[66:69], v37 offset0:112 offset1:120
	v_add_u32_e32 v37, 0x10000, v37
	ds_read_b64 v[74:75], v37
	s_waitcnt lgkmcnt(8)
	v_mov_b32_e32 v76, v38
	v_mov_b32_e32 v77, v40
	s_waitcnt lgkmcnt(7)
	v_mov_b32_e32 v78, v42
	v_mov_b32_e32 v79, v44
	s_waitcnt lgkmcnt(6)
	v_mov_b32_e32 v80, v46
	v_mov_b32_e32 v81, v48
	s_waitcnt lgkmcnt(5)
	v_mov_b32_e32 v82, v50
	v_mov_b32_e32 v83, v52
	s_waitcnt lgkmcnt(4)
	v_mov_b32_e32 v84, v54
	v_mov_b32_e32 v85, v56
	s_waitcnt lgkmcnt(3)
	v_mov_b32_e32 v86, v58
	v_mov_b32_e32 v87, v60
	s_waitcnt lgkmcnt(2)
	v_mov_b32_e32 v88, v62
	v_mov_b32_e32 v89, v64
	s_waitcnt lgkmcnt(1)
	v_mov_b32_e32 v90, v66
	v_mov_b32_e32 v91, v68
	s_add_i32 s14, s14, 8
	v_mov_b32_e32 v40, v39
	v_mov_b32_e32 v44, v43
	v_mov_b32_e32 v48, v47
	v_mov_b32_e32 v52, v51
	v_mov_b32_e32 v56, v55
	v_mov_b32_e32 v60, v59
	v_mov_b32_e32 v64, v63
	v_mov_b32_e32 v68, v67
	s_cmpk_eq_i32 s14, 0x200
	s_waitcnt vmcnt(29)
	v_pk_fma_f32 v[10:11], v[104:105], v[76:77], v[10:11] op_sel_hi:[0,1,1]
	v_pk_fma_f32 v[12:13], v[104:105], v[78:79], v[12:13] op_sel_hi:[0,1,1]
	v_pk_fma_f32 v[14:15], v[104:105], v[80:81], v[14:15] op_sel_hi:[0,1,1]
	v_pk_fma_f32 v[16:17], v[104:105], v[82:83], v[16:17] op_sel_hi:[0,1,1]
	v_pk_fma_f32 v[18:19], v[104:105], v[84:85], v[18:19] op_sel_hi:[0,1,1]
	v_pk_fma_f32 v[20:21], v[104:105], v[86:87], v[20:21] op_sel_hi:[0,1,1]
	v_pk_fma_f32 v[22:23], v[104:105], v[88:89], v[22:23] op_sel_hi:[0,1,1]
	v_pk_fma_f32 v[24:25], v[104:105], v[90:91], v[24:25] op_sel_hi:[0,1,1]
	s_waitcnt lgkmcnt(0)
	v_fmac_f32_e32 v2, v104, v74
	s_waitcnt vmcnt(28)
	v_pk_fma_f32 v[10:11], v[106:107], v[40:41], v[10:11] op_sel_hi:[0,1,1]
	v_pk_fma_f32 v[12:13], v[106:107], v[44:45], v[12:13] op_sel_hi:[0,1,1]
	v_pk_fma_f32 v[14:15], v[106:107], v[48:49], v[14:15] op_sel_hi:[0,1,1]
	v_pk_fma_f32 v[16:17], v[106:107], v[52:53], v[16:17] op_sel_hi:[0,1,1]
	v_pk_fma_f32 v[18:19], v[106:107], v[56:57], v[18:19] op_sel_hi:[0,1,1]
	v_pk_fma_f32 v[20:21], v[106:107], v[60:61], v[20:21] op_sel_hi:[0,1,1]
	v_pk_fma_f32 v[22:23], v[106:107], v[64:65], v[22:23] op_sel_hi:[0,1,1]
	v_pk_fma_f32 v[24:25], v[106:107], v[68:69], v[24:25] op_sel_hi:[0,1,1]
	v_fmac_f32_e32 v2, v106, v75
	v_add_u32_e32 v37, s14, v35
	ds_read2st64_b64 v[38:41], v37 offset1:8
	ds_read2st64_b64 v[42:45], v37 offset0:16 offset1:24
	ds_read2st64_b64 v[46:49], v37 offset0:32 offset1:40
	ds_read2st64_b64 v[50:53], v37 offset0:48 offset1:56
	ds_read2st64_b64 v[54:57], v37 offset0:64 offset1:72
	ds_read2st64_b64 v[58:61], v37 offset0:80 offset1:88
	ds_read2st64_b64 v[62:65], v37 offset0:96 offset1:104
	ds_read2st64_b64 v[66:69], v37 offset0:112 offset1:120
	v_add_u32_e32 v37, 0x10000, v37
	ds_read_b64 v[74:75], v37
	s_waitcnt lgkmcnt(8)
	v_mov_b32_e32 v76, v38
	v_mov_b32_e32 v77, v40
	s_waitcnt lgkmcnt(7)
	v_mov_b32_e32 v78, v42
	v_mov_b32_e32 v79, v44
	s_waitcnt lgkmcnt(6)
	v_mov_b32_e32 v80, v46
	v_mov_b32_e32 v81, v48
	s_waitcnt lgkmcnt(5)
	v_mov_b32_e32 v82, v50
	v_mov_b32_e32 v83, v52
	s_waitcnt lgkmcnt(4)
	v_mov_b32_e32 v84, v54
	v_mov_b32_e32 v85, v56
	s_waitcnt lgkmcnt(3)
	v_mov_b32_e32 v86, v58
	v_mov_b32_e32 v87, v60
	s_waitcnt lgkmcnt(2)
	v_mov_b32_e32 v88, v62
	v_mov_b32_e32 v89, v64
	s_waitcnt lgkmcnt(1)
	v_mov_b32_e32 v90, v66
	v_mov_b32_e32 v91, v68
	s_add_i32 s14, s14, 8
	v_mov_b32_e32 v40, v39
	v_mov_b32_e32 v44, v43
	v_mov_b32_e32 v48, v47
	v_mov_b32_e32 v52, v51
	v_mov_b32_e32 v56, v55
	v_mov_b32_e32 v60, v59
	v_mov_b32_e32 v64, v63
	v_mov_b32_e32 v68, v67
	s_cmpk_eq_i32 s14, 0x200
	s_waitcnt vmcnt(27)
	v_pk_fma_f32 v[10:11], v[108:109], v[76:77], v[10:11] op_sel_hi:[0,1,1]
	v_pk_fma_f32 v[12:13], v[108:109], v[78:79], v[12:13] op_sel_hi:[0,1,1]
	v_pk_fma_f32 v[14:15], v[108:109], v[80:81], v[14:15] op_sel_hi:[0,1,1]
	v_pk_fma_f32 v[16:17], v[108:109], v[82:83], v[16:17] op_sel_hi:[0,1,1]
	v_pk_fma_f32 v[18:19], v[108:109], v[84:85], v[18:19] op_sel_hi:[0,1,1]
	v_pk_fma_f32 v[20:21], v[108:109], v[86:87], v[20:21] op_sel_hi:[0,1,1]
	v_pk_fma_f32 v[22:23], v[108:109], v[88:89], v[22:23] op_sel_hi:[0,1,1]
	v_pk_fma_f32 v[24:25], v[108:109], v[90:91], v[24:25] op_sel_hi:[0,1,1]
	s_waitcnt lgkmcnt(0)
	v_fmac_f32_e32 v2, v108, v74
	s_waitcnt vmcnt(26)
; DEVI void ph_setup(const int wv, const Params& p, unsigned char* lds) {
;     ...
;             const float* w = p.in[6] + (size_t)l * 1024 * 6144 + n0 + n;
;             for (int k = kg * 128; k < kg * 128 + 128; ++k) { const float wv = w[(size_t)k * 6144];
; #pragma unroll
;                 for (int r = 0; r < 17; ++r) acc[r] += scv[r * 1024 + k] * wv; }
	v_pk_fma_f32 v[10:11], v[110:111], v[40:41], v[10:11] op_sel_hi:[0,1,1]
	v_pk_fma_f32 v[12:13], v[110:111], v[44:45], v[12:13] op_sel_hi:[0,1,1]
	v_pk_fma_f32 v[14:15], v[110:111], v[48:49], v[14:15] op_sel_hi:[0,1,1]
	v_pk_fma_f32 v[16:17], v[110:111], v[52:53], v[16:17] op_sel_hi:[0,1,1]
	v_pk_fma_f32 v[18:19], v[110:111], v[56:57], v[18:19] op_sel_hi:[0,1,1]
	v_pk_fma_f32 v[20:21], v[110:111], v[60:61], v[20:21] op_sel_hi:[0,1,1]
	v_pk_fma_f32 v[22:23], v[110:111], v[64:65], v[22:23] op_sel_hi:[0,1,1]
	v_pk_fma_f32 v[24:25], v[110:111], v[68:69], v[24:25] op_sel_hi:[0,1,1]
	v_fmac_f32_e32 v2, v110, v75
	v_add_u32_e32 v37, s14, v35
	ds_read2st64_b64 v[38:41], v37 offset1:8
	ds_read2st64_b64 v[42:45], v37 offset0:16 offset1:24
	ds_read2st64_b64 v[46:49], v37 offset0:32 offset1:40
	ds_read2st64_b64 v[50:53], v37 offset0:48 offset1:56
	ds_read2st64_b64 v[54:57], v37 offset0:64 offset1:72
	ds_read2st64_b64 v[58:61], v37 offset0:80 offset1:88
	ds_read2st64_b64 v[62:65], v37 offset0:96 offset1:104
	ds_read2st64_b64 v[66:69], v37 offset0:112 offset1:120
	v_add_u32_e32 v37, 0x10000, v37
	ds_read_b64 v[74:75], v37
	s_waitcnt lgkmcnt(8)
	v_mov_b32_e32 v76, v38
	v_mov_b32_e32 v77, v40
	s_waitcnt lgkmcnt(7)
	v_mov_b32_e32 v78, v42
	v_mov_b32_e32 v79, v44
	s_waitcnt lgkmcnt(6)
	v_mov_b32_e32 v80, v46
	v_mov_b32_e32 v81, v48
	s_waitcnt lgkmcnt(5)
	v_mov_b32_e32 v82, v50
	v_mov_b32_e32 v83, v52
	s_waitcnt lgkmcnt(4)
	v_mov_b32_e32 v84, v54
	v_mov_b32_e32 v85, v56
	s_waitcnt lgkmcnt(3)
	v_mov_b32_e32 v86, v58
	v_mov_b32_e32 v87, v60
	s_waitcnt lgkmcnt(2)
	v_mov_b32_e32 v88, v62
	v_mov_b32_e32 v89, v64
	s_waitcnt lgkmcnt(1)
	v_mov_b32_e32 v90, v66
	v_mov_b32_e32 v91, v68
	s_add_i32 s14, s14, 8
	v_mov_b32_e32 v40, v39
	v_mov_b32_e32 v44, v43
	v_mov_b32_e32 v48, v47
	v_mov_b32_e32 v52, v51
	v_mov_b32_e32 v56, v55
	v_mov_b32_e32 v60, v59
	v_mov_b32_e32 v64, v63
	v_mov_b32_e32 v68, v67
	s_cmpk_eq_i32 s14, 0x200
	s_waitcnt vmcnt(25)
	v_pk_fma_f32 v[10:11], v[112:113], v[76:77], v[10:11] op_sel_hi:[0,1,1]
	v_pk_fma_f32 v[12:13], v[112:113], v[78:79], v[12:13] op_sel_hi:[0,1,1]
	v_pk_fma_f32 v[14:15], v[112:113], v[80:81], v[14:15] op_sel_hi:[0,1,1]
	v_pk_fma_f32 v[16:17], v[112:113], v[82:83], v[16:17] op_sel_hi:[0,1,1]
	v_pk_fma_f32 v[18:19], v[112:113], v[84:85], v[18:19] op_sel_hi:[0,1,1]
	v_pk_fma_f32 v[20:21], v[112:113], v[86:87], v[20:21] op_sel_hi:[0,1,1]
	v_pk_fma_f32 v[22:23], v[112:113], v[88:89], v[22:23] op_sel_hi:[0,1,1]
	v_pk_fma_f32 v[24:25], v[112:113], v[90:91], v[24:25] op_sel_hi:[0,1,1]
	s_waitcnt lgkmcnt(0)
	v_fmac_f32_e32 v2, v112, v74
	s_waitcnt vmcnt(24)
	v_pk_fma_f32 v[10:11], v[114:115], v[40:41], v[10:11] op_sel_hi:[0,1,1]
	v_pk_fma_f32 v[12:13], v[114:115], v[44:45], v[12:13] op_sel_hi:[0,1,1]
	v_pk_fma_f32 v[14:15], v[114:115], v[48:49], v[14:15] op_sel_hi:[0,1,1]
	v_pk_fma_f32 v[16:17], v[114:115], v[52:53], v[16:17] op_sel_hi:[0,1,1]
	v_pk_fma_f32 v[18:19], v[114:115], v[56:57], v[18:19] op_sel_hi:[0,1,1]
	v_pk_fma_f32 v[20:21], v[114:115], v[60:61], v[20:21] op_sel_hi:[0,1,1]
	v_pk_fma_f32 v[22:23], v[114:115], v[64:65], v[22:23] op_sel_hi:[0,1,1]
	v_pk_fma_f32 v[24:25], v[114:115], v[68:69], v[24:25] op_sel_hi:[0,1,1]
	v_fmac_f32_e32 v2, v114, v75
	v_add_u32_e32 v37, s14, v35
	ds_read2st64_b64 v[38:41], v37 offset1:8
	ds_read2st64_b64 v[42:45], v37 offset0:16 offset1:24
	ds_read2st64_b64 v[46:49], v37 offset0:32 offset1:40
	ds_read2st64_b64 v[50:53], v37 offset0:48 offset1:56
	ds_read2st64_b64 v[54:57], v37 offset0:64 offset1:72
	ds_read2st64_b64 v[58:61], v37 offset0:80 offset1:88
	ds_read2st64_b64 v[62:65], v37 offset0:96 offset1:104
	ds_read2st64_b64 v[66:69], v37 offset0:112 offset1:120
	v_add_u32_e32 v37, 0x10000, v37
	ds_read_b64 v[74:75], v37
	s_waitcnt lgkmcnt(8)
	v_mov_b32_e32 v76, v38
	v_mov_b32_e32 v77, v40
	s_waitcnt lgkmcnt(7)
	v_mov_b32_e32 v78, v42
	v_mov_b32_e32 v79, v44
	s_waitcnt lgkmcnt(6)
	v_mov_b32_e32 v80, v46
	v_mov_b32_e32 v81, v48
	s_waitcnt lgkmcnt(5)
	v_mov_b32_e32 v82, v50
	v_mov_b32_e32 v83, v52
	s_waitcnt lgkmcnt(4)
	v_mov_b32_e32 v84, v54
	v_mov_b32_e32 v85, v56
	s_waitcnt lgkmcnt(3)
	v_mov_b32_e32 v86, v58
	v_mov_b32_e32 v87, v60
	s_waitcnt lgkmcnt(2)
	v_mov_b32_e32 v88, v62
	v_mov_b32_e32 v89, v64
	s_waitcnt lgkmcnt(1)
	v_mov_b32_e32 v90, v66
	v_mov_b32_e32 v91, v68
	s_add_i32 s14, s14, 8
	v_mov_b32_e32 v40, v39
	v_mov_b32_e32 v44, v43
	v_mov_b32_e32 v48, v47
	v_mov_b32_e32 v52, v51
	v_mov_b32_e32 v56, v55
	v_mov_b32_e32 v60, v59
	v_mov_b32_e32 v64, v63
	v_mov_b32_e32 v68, v67
	s_cmpk_eq_i32 s14, 0x200
	s_waitcnt vmcnt(23)
	v_pk_fma_f32 v[10:11], v[116:117], v[76:77], v[10:11] op_sel_hi:[0,1,1]
	v_pk_fma_f32 v[12:13], v[116:117], v[78:79], v[12:13] op_sel_hi:[0,1,1]
	v_pk_fma_f32 v[14:15], v[116:117], v[80:81], v[14:15] op_sel_hi:[0,1,1]
	v_pk_fma_f32 v[16:17], v[116:117], v[82:83], v[16:17] op_sel_hi:[0,1,1]
	v_pk_fma_f32 v[18:19], v[116:117], v[84:85], v[18:19] op_sel_hi:[0,1,1]
	v_pk_fma_f32 v[20:21], v[116:117], v[86:87], v[20:21] op_sel_hi:[0,1,1]
	v_pk_fma_f32 v[22:23], v[116:117], v[88:89], v[22:23] op_sel_hi:[0,1,1]
	v_pk_fma_f32 v[24:25], v[116:117], v[90:91], v[24:25] op_sel_hi:[0,1,1]
	s_waitcnt lgkmcnt(0)
	v_fmac_f32_e32 v2, v116, v74
	s_waitcnt vmcnt(22)
; DEVI void ph_setup(const int wv, const Params& p, unsigned char* lds) {
;     ...
;             const float* w = p.in[6] + (size_t)l * 1024 * 6144 + n0 + n;
;             for (int k = kg * 128; k < kg * 128 + 128; ++k) { const float wv = w[(size_t)k * 6144];
; #pragma unroll
;                 for (int r = 0; r < 17; ++r) acc[r] += scv[r * 1024 + k] * wv; }
	v_pk_fma_f32 v[10:11], v[118:119], v[40:41], v[10:11] op_sel_hi:[0,1,1]
	v_pk_fma_f32 v[12:13], v[118:119], v[44:45], v[12:13] op_sel_hi:[0,1,1]
	v_pk_fma_f32 v[14:15], v[118:119], v[48:49], v[14:15] op_sel_hi:[0,1,1]
	v_pk_fma_f32 v[16:17], v[118:119], v[52:53], v[16:17] op_sel_hi:[0,1,1]
	v_pk_fma_f32 v[18:19], v[118:119], v[56:57], v[18:19] op_sel_hi:[0,1,1]
	v_pk_fma_f32 v[20:21], v[118:119], v[60:61], v[20:21] op_sel_hi:[0,1,1]
	v_pk_fma_f32 v[22:23], v[118:119], v[64:65], v[22:23] op_sel_hi:[0,1,1]
	v_pk_fma_f32 v[24:25], v[118:119], v[68:69], v[24:25] op_sel_hi:[0,1,1]
	v_fmac_f32_e32 v2, v118, v75
	v_add_u32_e32 v37, s14, v35
	ds_read2st64_b64 v[38:41], v37 offset1:8
	ds_read2st64_b64 v[42:45], v37 offset0:16 offset1:24
	ds_read2st64_b64 v[46:49], v37 offset0:32 offset1:40
	ds_read2st64_b64 v[50:53], v37 offset0:48 offset1:56
	ds_read2st64_b64 v[54:57], v37 offset0:64 offset1:72
	ds_read2st64_b64 v[58:61], v37 offset0:80 offset1:88
	ds_read2st64_b64 v[62:65], v37 offset0:96 offset1:104
	ds_read2st64_b64 v[66:69], v37 offset0:112 offset1:120
	v_add_u32_e32 v37, 0x10000, v37
	ds_read_b64 v[74:75], v37
	s_waitcnt lgkmcnt(8)
	v_mov_b32_e32 v76, v38
	v_mov_b32_e32 v77, v40
	s_waitcnt lgkmcnt(7)
	v_mov_b32_e32 v78, v42
	v_mov_b32_e32 v79, v44
	s_waitcnt lgkmcnt(6)
	v_mov_b32_e32 v80, v46
	v_mov_b32_e32 v81, v48
	s_waitcnt lgkmcnt(5)
	v_mov_b32_e32 v82, v50
	v_mov_b32_e32 v83, v52
	s_waitcnt lgkmcnt(4)
	v_mov_b32_e32 v84, v54
	v_mov_b32_e32 v85, v56
	s_waitcnt lgkmcnt(3)
	v_mov_b32_e32 v86, v58
	v_mov_b32_e32 v87, v60
	s_waitcnt lgkmcnt(2)
	v_mov_b32_e32 v88, v62
	v_mov_b32_e32 v89, v64
	s_waitcnt lgkmcnt(1)
	v_mov_b32_e32 v90, v66
	v_mov_b32_e32 v91, v68
	s_add_i32 s14, s14, 8
	v_mov_b32_e32 v40, v39
	v_mov_b32_e32 v44, v43
	v_mov_b32_e32 v48, v47
	v_mov_b32_e32 v52, v51
	v_mov_b32_e32 v56, v55
	v_mov_b32_e32 v60, v59
	v_mov_b32_e32 v64, v63
	v_mov_b32_e32 v68, v67
	s_cmpk_eq_i32 s14, 0x200
	s_waitcnt vmcnt(21)
	v_pk_fma_f32 v[10:11], v[120:121], v[76:77], v[10:11] op_sel_hi:[0,1,1]
	v_pk_fma_f32 v[12:13], v[120:121], v[78:79], v[12:13] op_sel_hi:[0,1,1]
	v_pk_fma_f32 v[14:15], v[120:121], v[80:81], v[14:15] op_sel_hi:[0,1,1]
	v_pk_fma_f32 v[16:17], v[120:121], v[82:83], v[16:17] op_sel_hi:[0,1,1]
	v_pk_fma_f32 v[18:19], v[120:121], v[84:85], v[18:19] op_sel_hi:[0,1,1]
	v_pk_fma_f32 v[20:21], v[120:121], v[86:87], v[20:21] op_sel_hi:[0,1,1]
	v_pk_fma_f32 v[22:23], v[120:121], v[88:89], v[22:23] op_sel_hi:[0,1,1]
	v_pk_fma_f32 v[24:25], v[120:121], v[90:91], v[24:25] op_sel_hi:[0,1,1]
	s_waitcnt lgkmcnt(0)
	v_fmac_f32_e32 v2, v120, v74
	s_waitcnt vmcnt(20)
	v_pk_fma_f32 v[10:11], v[122:123], v[40:41], v[10:11] op_sel_hi:[0,1,1]
	v_pk_fma_f32 v[12:13], v[122:123], v[44:45], v[12:13] op_sel_hi:[0,1,1]
	v_pk_fma_f32 v[14:15], v[122:123], v[48:49], v[14:15] op_sel_hi:[0,1,1]
	v_pk_fma_f32 v[16:17], v[122:123], v[52:53], v[16:17] op_sel_hi:[0,1,1]
	v_pk_fma_f32 v[18:19], v[122:123], v[56:57], v[18:19] op_sel_hi:[0,1,1]
	v_pk_fma_f32 v[20:21], v[122:123], v[60:61], v[20:21] op_sel_hi:[0,1,1]
	v_pk_fma_f32 v[22:23], v[122:123], v[64:65], v[22:23] op_sel_hi:[0,1,1]
	v_pk_fma_f32 v[24:25], v[122:123], v[68:69], v[24:25] op_sel_hi:[0,1,1]
	v_fmac_f32_e32 v2, v122, v75
	v_add_u32_e32 v37, s14, v35
	ds_read2st64_b64 v[38:41], v37 offset1:8
	ds_read2st64_b64 v[42:45], v37 offset0:16 offset1:24
	ds_read2st64_b64 v[46:49], v37 offset0:32 offset1:40
	ds_read2st64_b64 v[50:53], v37 offset0:48 offset1:56
	ds_read2st64_b64 v[54:57], v37 offset0:64 offset1:72
	ds_read2st64_b64 v[58:61], v37 offset0:80 offset1:88
	ds_read2st64_b64 v[62:65], v37 offset0:96 offset1:104
	ds_read2st64_b64 v[66:69], v37 offset0:112 offset1:120
	v_add_u32_e32 v37, 0x10000, v37
	ds_read_b64 v[74:75], v37
	s_waitcnt lgkmcnt(8)
	v_mov_b32_e32 v76, v38
	v_mov_b32_e32 v77, v40
	s_waitcnt lgkmcnt(7)
	v_mov_b32_e32 v78, v42
	v_mov_b32_e32 v79, v44
	s_waitcnt lgkmcnt(6)
	v_mov_b32_e32 v80, v46
	v_mov_b32_e32 v81, v48
	s_waitcnt lgkmcnt(5)
	v_mov_b32_e32 v82, v50
	v_mov_b32_e32 v83, v52
	s_waitcnt lgkmcnt(4)
	v_mov_b32_e32 v84, v54
	v_mov_b32_e32 v85, v56
	s_waitcnt lgkmcnt(3)
	v_mov_b32_e32 v86, v58
	v_mov_b32_e32 v87, v60
	s_waitcnt lgkmcnt(2)
	v_mov_b32_e32 v88, v62
	v_mov_b32_e32 v89, v64
	s_waitcnt lgkmcnt(1)
	v_mov_b32_e32 v90, v66
	v_mov_b32_e32 v91, v68
	s_add_i32 s14, s14, 8
	v_mov_b32_e32 v40, v39
	v_mov_b32_e32 v44, v43
	v_mov_b32_e32 v48, v47
	v_mov_b32_e32 v52, v51
	v_mov_b32_e32 v56, v55
	v_mov_b32_e32 v60, v59
	v_mov_b32_e32 v64, v63
	v_mov_b32_e32 v68, v67
	s_cmpk_eq_i32 s14, 0x200
	s_waitcnt vmcnt(19)
	v_pk_fma_f32 v[10:11], v[124:125], v[76:77], v[10:11] op_sel_hi:[0,1,1]
	v_pk_fma_f32 v[12:13], v[124:125], v[78:79], v[12:13] op_sel_hi:[0,1,1]
	v_pk_fma_f32 v[14:15], v[124:125], v[80:81], v[14:15] op_sel_hi:[0,1,1]
	v_pk_fma_f32 v[16:17], v[124:125], v[82:83], v[16:17] op_sel_hi:[0,1,1]
	v_pk_fma_f32 v[18:19], v[124:125], v[84:85], v[18:19] op_sel_hi:[0,1,1]
	v_pk_fma_f32 v[20:21], v[124:125], v[86:87], v[20:21] op_sel_hi:[0,1,1]
	v_pk_fma_f32 v[22:23], v[124:125], v[88:89], v[22:23] op_sel_hi:[0,1,1]
	v_pk_fma_f32 v[24:25], v[124:125], v[90:91], v[24:25] op_sel_hi:[0,1,1]
	s_waitcnt lgkmcnt(0)
	v_fmac_f32_e32 v2, v124, v74
	s_waitcnt vmcnt(18)
; DEVI void ph_setup(const int wv, const Params& p, unsigned char* lds) {
;     ...
;             const float* w = p.in[6] + (size_t)l * 1024 * 6144 + n0 + n;
;             for (int k = kg * 128; k < kg * 128 + 128; ++k) { const float wv = w[(size_t)k * 6144];
; #pragma unroll
;                 for (int r = 0; r < 17; ++r) acc[r] += scv[r * 1024 + k] * wv; }
	v_pk_fma_f32 v[10:11], v[126:127], v[40:41], v[10:11] op_sel_hi:[0,1,1]
	v_pk_fma_f32 v[12:13], v[126:127], v[44:45], v[12:13] op_sel_hi:[0,1,1]
	v_pk_fma_f32 v[14:15], v[126:127], v[48:49], v[14:15] op_sel_hi:[0,1,1]
	v_pk_fma_f32 v[16:17], v[126:127], v[52:53], v[16:17] op_sel_hi:[0,1,1]
	v_pk_fma_f32 v[18:19], v[126:127], v[56:57], v[18:19] op_sel_hi:[0,1,1]
	v_pk_fma_f32 v[20:21], v[126:127], v[60:61], v[20:21] op_sel_hi:[0,1,1]
	v_pk_fma_f32 v[22:23], v[126:127], v[64:65], v[22:23] op_sel_hi:[0,1,1]
	v_pk_fma_f32 v[24:25], v[126:127], v[68:69], v[24:25] op_sel_hi:[0,1,1]
	v_fmac_f32_e32 v2, v126, v75
	v_add_u32_e32 v37, s14, v35
	ds_read2st64_b64 v[38:41], v37 offset1:8
	ds_read2st64_b64 v[42:45], v37 offset0:16 offset1:24
	ds_read2st64_b64 v[46:49], v37 offset0:32 offset1:40
	ds_read2st64_b64 v[50:53], v37 offset0:48 offset1:56
	ds_read2st64_b64 v[54:57], v37 offset0:64 offset1:72
	ds_read2st64_b64 v[58:61], v37 offset0:80 offset1:88
	ds_read2st64_b64 v[62:65], v37 offset0:96 offset1:104
	ds_read2st64_b64 v[66:69], v37 offset0:112 offset1:120
	v_add_u32_e32 v37, 0x10000, v37
	ds_read_b64 v[74:75], v37
	s_waitcnt lgkmcnt(8)
	v_mov_b32_e32 v76, v38
	v_mov_b32_e32 v77, v40
	s_waitcnt lgkmcnt(7)
	v_mov_b32_e32 v78, v42
	v_mov_b32_e32 v79, v44
	s_waitcnt lgkmcnt(6)
	v_mov_b32_e32 v80, v46
	v_mov_b32_e32 v81, v48
	s_waitcnt lgkmcnt(5)
	v_mov_b32_e32 v82, v50
	v_mov_b32_e32 v83, v52
	s_waitcnt lgkmcnt(4)
	v_mov_b32_e32 v84, v54
	v_mov_b32_e32 v85, v56
	s_waitcnt lgkmcnt(3)
	v_mov_b32_e32 v86, v58
	v_mov_b32_e32 v87, v60
	s_waitcnt lgkmcnt(2)
	v_mov_b32_e32 v88, v62
	v_mov_b32_e32 v89, v64
	s_waitcnt lgkmcnt(1)
	v_mov_b32_e32 v90, v66
	v_mov_b32_e32 v91, v68
	s_add_i32 s14, s14, 8
	v_mov_b32_e32 v40, v39
	v_mov_b32_e32 v44, v43
	v_mov_b32_e32 v48, v47
	v_mov_b32_e32 v52, v51
	v_mov_b32_e32 v56, v55
	v_mov_b32_e32 v60, v59
	v_mov_b32_e32 v64, v63
	v_mov_b32_e32 v68, v67
	s_cmpk_eq_i32 s14, 0x200
	s_waitcnt vmcnt(17)
	v_pk_fma_f32 v[10:11], v[128:129], v[76:77], v[10:11] op_sel_hi:[0,1,1]
	v_pk_fma_f32 v[12:13], v[128:129], v[78:79], v[12:13] op_sel_hi:[0,1,1]
	v_pk_fma_f32 v[14:15], v[128:129], v[80:81], v[14:15] op_sel_hi:[0,1,1]
	v_pk_fma_f32 v[16:17], v[128:129], v[82:83], v[16:17] op_sel_hi:[0,1,1]
	v_pk_fma_f32 v[18:19], v[128:129], v[84:85], v[18:19] op_sel_hi:[0,1,1]
	v_pk_fma_f32 v[20:21], v[128:129], v[86:87], v[20:21] op_sel_hi:[0,1,1]
	v_pk_fma_f32 v[22:23], v[128:129], v[88:89], v[22:23] op_sel_hi:[0,1,1]
	v_pk_fma_f32 v[24:25], v[128:129], v[90:91], v[24:25] op_sel_hi:[0,1,1]
	s_waitcnt lgkmcnt(0)
	v_fmac_f32_e32 v2, v128, v74
	s_waitcnt vmcnt(16)
	v_pk_fma_f32 v[10:11], v[130:131], v[40:41], v[10:11] op_sel_hi:[0,1,1]
	v_pk_fma_f32 v[12:13], v[130:131], v[44:45], v[12:13] op_sel_hi:[0,1,1]
	v_pk_fma_f32 v[14:15], v[130:131], v[48:49], v[14:15] op_sel_hi:[0,1,1]
	v_pk_fma_f32 v[16:17], v[130:131], v[52:53], v[16:17] op_sel_hi:[0,1,1]
	v_pk_fma_f32 v[18:19], v[130:131], v[56:57], v[18:19] op_sel_hi:[0,1,1]
	v_pk_fma_f32 v[20:21], v[130:131], v[60:61], v[20:21] op_sel_hi:[0,1,1]
	v_pk_fma_f32 v[22:23], v[130:131], v[64:65], v[22:23] op_sel_hi:[0,1,1]
	v_pk_fma_f32 v[24:25], v[130:131], v[68:69], v[24:25] op_sel_hi:[0,1,1]
	v_fmac_f32_e32 v2, v130, v75
	v_add_u32_e32 v37, s14, v35
	ds_read2st64_b64 v[38:41], v37 offset1:8
	ds_read2st64_b64 v[42:45], v37 offset0:16 offset1:24
	ds_read2st64_b64 v[46:49], v37 offset0:32 offset1:40
	ds_read2st64_b64 v[50:53], v37 offset0:48 offset1:56
	ds_read2st64_b64 v[54:57], v37 offset0:64 offset1:72
	ds_read2st64_b64 v[58:61], v37 offset0:80 offset1:88
	ds_read2st64_b64 v[62:65], v37 offset0:96 offset1:104
	ds_read2st64_b64 v[66:69], v37 offset0:112 offset1:120
	v_add_u32_e32 v37, 0x10000, v37
	ds_read_b64 v[74:75], v37
	s_waitcnt lgkmcnt(8)
	v_mov_b32_e32 v76, v38
	v_mov_b32_e32 v77, v40
	s_waitcnt lgkmcnt(7)
	v_mov_b32_e32 v78, v42
	v_mov_b32_e32 v79, v44
	s_waitcnt lgkmcnt(6)
	v_mov_b32_e32 v80, v46
	v_mov_b32_e32 v81, v48
	s_waitcnt lgkmcnt(5)
	v_mov_b32_e32 v82, v50
	v_mov_b32_e32 v83, v52
	s_waitcnt lgkmcnt(4)
	v_mov_b32_e32 v84, v54
	v_mov_b32_e32 v85, v56
	s_waitcnt lgkmcnt(3)
	v_mov_b32_e32 v86, v58
	v_mov_b32_e32 v87, v60
	s_waitcnt lgkmcnt(2)
	v_mov_b32_e32 v88, v62
	v_mov_b32_e32 v89, v64
	s_waitcnt lgkmcnt(1)
	v_mov_b32_e32 v90, v66
	v_mov_b32_e32 v91, v68
	s_add_i32 s14, s14, 8
	v_mov_b32_e32 v40, v39
	v_mov_b32_e32 v44, v43
	v_mov_b32_e32 v48, v47
	v_mov_b32_e32 v52, v51
	v_mov_b32_e32 v56, v55
	v_mov_b32_e32 v60, v59
	v_mov_b32_e32 v64, v63
	v_mov_b32_e32 v68, v67
	s_cmpk_eq_i32 s14, 0x200
	s_waitcnt vmcnt(15)
	v_pk_fma_f32 v[10:11], v[132:133], v[76:77], v[10:11] op_sel_hi:[0,1,1]
	v_pk_fma_f32 v[12:13], v[132:133], v[78:79], v[12:13] op_sel_hi:[0,1,1]
	v_pk_fma_f32 v[14:15], v[132:133], v[80:81], v[14:15] op_sel_hi:[0,1,1]
	v_pk_fma_f32 v[16:17], v[132:133], v[82:83], v[16:17] op_sel_hi:[0,1,1]
	v_pk_fma_f32 v[18:19], v[132:133], v[84:85], v[18:19] op_sel_hi:[0,1,1]
	v_pk_fma_f32 v[20:21], v[132:133], v[86:87], v[20:21] op_sel_hi:[0,1,1]
	v_pk_fma_f32 v[22:23], v[132:133], v[88:89], v[22:23] op_sel_hi:[0,1,1]
	v_pk_fma_f32 v[24:25], v[132:133], v[90:91], v[24:25] op_sel_hi:[0,1,1]
	s_waitcnt lgkmcnt(0)
	v_fmac_f32_e32 v2, v132, v74
	s_waitcnt vmcnt(14)
; DEVI void ph_setup(const int wv, const Params& p, unsigned char* lds) {
;     ...
;             const float* w = p.in[6] + (size_t)l * 1024 * 6144 + n0 + n;
;             for (int k = kg * 128; k < kg * 128 + 128; ++k) { const float wv = w[(size_t)k * 6144];
; #pragma unroll
;                 for (int r = 0; r < 17; ++r) acc[r] += scv[r * 1024 + k] * wv; }
	v_pk_fma_f32 v[10:11], v[134:135], v[40:41], v[10:11] op_sel_hi:[0,1,1]
	v_pk_fma_f32 v[12:13], v[134:135], v[44:45], v[12:13] op_sel_hi:[0,1,1]
	v_pk_fma_f32 v[14:15], v[134:135], v[48:49], v[14:15] op_sel_hi:[0,1,1]
	v_pk_fma_f32 v[16:17], v[134:135], v[52:53], v[16:17] op_sel_hi:[0,1,1]
	v_pk_fma_f32 v[18:19], v[134:135], v[56:57], v[18:19] op_sel_hi:[0,1,1]
	v_pk_fma_f32 v[20:21], v[134:135], v[60:61], v[20:21] op_sel_hi:[0,1,1]
	v_pk_fma_f32 v[22:23], v[134:135], v[64:65], v[22:23] op_sel_hi:[0,1,1]
	v_pk_fma_f32 v[24:25], v[134:135], v[68:69], v[24:25] op_sel_hi:[0,1,1]
	v_fmac_f32_e32 v2, v134, v75
	v_add_u32_e32 v37, s14, v35
	ds_read2st64_b64 v[38:41], v37 offset1:8
	ds_read2st64_b64 v[42:45], v37 offset0:16 offset1:24
	ds_read2st64_b64 v[46:49], v37 offset0:32 offset1:40
	ds_read2st64_b64 v[50:53], v37 offset0:48 offset1:56
	ds_read2st64_b64 v[54:57], v37 offset0:64 offset1:72
	ds_read2st64_b64 v[58:61], v37 offset0:80 offset1:88
	ds_read2st64_b64 v[62:65], v37 offset0:96 offset1:104
	ds_read2st64_b64 v[66:69], v37 offset0:112 offset1:120
	v_add_u32_e32 v37, 0x10000, v37
	ds_read_b64 v[74:75], v37
	s_waitcnt lgkmcnt(8)
	v_mov_b32_e32 v76, v38
	v_mov_b32_e32 v77, v40
	s_waitcnt lgkmcnt(7)
	v_mov_b32_e32 v78, v42
	v_mov_b32_e32 v79, v44
	s_waitcnt lgkmcnt(6)
	v_mov_b32_e32 v80, v46
	v_mov_b32_e32 v81, v48
	s_waitcnt lgkmcnt(5)
	v_mov_b32_e32 v82, v50
	v_mov_b32_e32 v83, v52
	s_waitcnt lgkmcnt(4)
	v_mov_b32_e32 v84, v54
	v_mov_b32_e32 v85, v56
	s_waitcnt lgkmcnt(3)
	v_mov_b32_e32 v86, v58
	v_mov_b32_e32 v87, v60
	s_waitcnt lgkmcnt(2)
	v_mov_b32_e32 v88, v62
	v_mov_b32_e32 v89, v64
	s_waitcnt lgkmcnt(1)
	v_mov_b32_e32 v90, v66
	v_mov_b32_e32 v91, v68
	s_add_i32 s14, s14, 8
	v_mov_b32_e32 v40, v39
	v_mov_b32_e32 v44, v43
	v_mov_b32_e32 v48, v47
	v_mov_b32_e32 v52, v51
	v_mov_b32_e32 v56, v55
	v_mov_b32_e32 v60, v59
	v_mov_b32_e32 v64, v63
	v_mov_b32_e32 v68, v67
	s_cmpk_eq_i32 s14, 0x200
	s_waitcnt vmcnt(13)
	v_pk_fma_f32 v[10:11], v[136:137], v[76:77], v[10:11] op_sel_hi:[0,1,1]
	v_pk_fma_f32 v[12:13], v[136:137], v[78:79], v[12:13] op_sel_hi:[0,1,1]
	v_pk_fma_f32 v[14:15], v[136:137], v[80:81], v[14:15] op_sel_hi:[0,1,1]
	v_pk_fma_f32 v[16:17], v[136:137], v[82:83], v[16:17] op_sel_hi:[0,1,1]
	v_pk_fma_f32 v[18:19], v[136:137], v[84:85], v[18:19] op_sel_hi:[0,1,1]
	v_pk_fma_f32 v[20:21], v[136:137], v[86:87], v[20:21] op_sel_hi:[0,1,1]
	v_pk_fma_f32 v[22:23], v[136:137], v[88:89], v[22:23] op_sel_hi:[0,1,1]
	v_pk_fma_f32 v[24:25], v[136:137], v[90:91], v[24:25] op_sel_hi:[0,1,1]
	s_waitcnt lgkmcnt(0)
	v_fmac_f32_e32 v2, v136, v74
	s_waitcnt vmcnt(12)
	v_pk_fma_f32 v[10:11], v[138:139], v[40:41], v[10:11] op_sel_hi:[0,1,1]
	v_pk_fma_f32 v[12:13], v[138:139], v[44:45], v[12:13] op_sel_hi:[0,1,1]
	v_pk_fma_f32 v[14:15], v[138:139], v[48:49], v[14:15] op_sel_hi:[0,1,1]
	v_pk_fma_f32 v[16:17], v[138:139], v[52:53], v[16:17] op_sel_hi:[0,1,1]
	v_pk_fma_f32 v[18:19], v[138:139], v[56:57], v[18:19] op_sel_hi:[0,1,1]
	v_pk_fma_f32 v[20:21], v[138:139], v[60:61], v[20:21] op_sel_hi:[0,1,1]
	v_pk_fma_f32 v[22:23], v[138:139], v[64:65], v[22:23] op_sel_hi:[0,1,1]
	v_pk_fma_f32 v[24:25], v[138:139], v[68:69], v[24:25] op_sel_hi:[0,1,1]
	v_fmac_f32_e32 v2, v138, v75
	v_add_u32_e32 v37, s14, v35
	ds_read2st64_b64 v[38:41], v37 offset1:8
	ds_read2st64_b64 v[42:45], v37 offset0:16 offset1:24
	ds_read2st64_b64 v[46:49], v37 offset0:32 offset1:40
	ds_read2st64_b64 v[50:53], v37 offset0:48 offset1:56
	ds_read2st64_b64 v[54:57], v37 offset0:64 offset1:72
	ds_read2st64_b64 v[58:61], v37 offset0:80 offset1:88
	ds_read2st64_b64 v[62:65], v37 offset0:96 offset1:104
	ds_read2st64_b64 v[66:69], v37 offset0:112 offset1:120
	v_add_u32_e32 v37, 0x10000, v37
	ds_read_b64 v[74:75], v37
	s_waitcnt lgkmcnt(8)
	v_mov_b32_e32 v76, v38
	v_mov_b32_e32 v77, v40
	s_waitcnt lgkmcnt(7)
	v_mov_b32_e32 v78, v42
	v_mov_b32_e32 v79, v44
	s_waitcnt lgkmcnt(6)
	v_mov_b32_e32 v80, v46
	v_mov_b32_e32 v81, v48
	s_waitcnt lgkmcnt(5)
	v_mov_b32_e32 v82, v50
	v_mov_b32_e32 v83, v52
	s_waitcnt lgkmcnt(4)
	v_mov_b32_e32 v84, v54
	v_mov_b32_e32 v85, v56
	s_waitcnt lgkmcnt(3)
	v_mov_b32_e32 v86, v58
	v_mov_b32_e32 v87, v60
	s_waitcnt lgkmcnt(2)
	v_mov_b32_e32 v88, v62
	v_mov_b32_e32 v89, v64
	s_waitcnt lgkmcnt(1)
	v_mov_b32_e32 v90, v66
	v_mov_b32_e32 v91, v68
	s_add_i32 s14, s14, 8
	v_mov_b32_e32 v40, v39
	v_mov_b32_e32 v44, v43
	v_mov_b32_e32 v48, v47
	v_mov_b32_e32 v52, v51
	v_mov_b32_e32 v56, v55
	v_mov_b32_e32 v60, v59
	v_mov_b32_e32 v64, v63
	v_mov_b32_e32 v68, v67
	s_cmpk_eq_i32 s14, 0x200
	s_waitcnt vmcnt(11)
	v_pk_fma_f32 v[10:11], v[140:141], v[76:77], v[10:11] op_sel_hi:[0,1,1]
	v_pk_fma_f32 v[12:13], v[140:141], v[78:79], v[12:13] op_sel_hi:[0,1,1]
	v_pk_fma_f32 v[14:15], v[140:141], v[80:81], v[14:15] op_sel_hi:[0,1,1]
	v_pk_fma_f32 v[16:17], v[140:141], v[82:83], v[16:17] op_sel_hi:[0,1,1]
	v_pk_fma_f32 v[18:19], v[140:141], v[84:85], v[18:19] op_sel_hi:[0,1,1]
	v_pk_fma_f32 v[20:21], v[140:141], v[86:87], v[20:21] op_sel_hi:[0,1,1]
	v_pk_fma_f32 v[22:23], v[140:141], v[88:89], v[22:23] op_sel_hi:[0,1,1]
	v_pk_fma_f32 v[24:25], v[140:141], v[90:91], v[24:25] op_sel_hi:[0,1,1]
	s_waitcnt lgkmcnt(0)
	v_fmac_f32_e32 v2, v140, v74
	s_waitcnt vmcnt(10)
; DEVI void ph_setup(const int wv, const Params& p, unsigned char* lds) {
;     ...
;             const float* w = p.in[6] + (size_t)l * 1024 * 6144 + n0 + n;
;             for (int k = kg * 128; k < kg * 128 + 128; ++k) { const float wv = w[(size_t)k * 6144];
; #pragma unroll
;                 for (int r = 0; r < 17; ++r) acc[r] += scv[r * 1024 + k] * wv; }
	v_pk_fma_f32 v[10:11], v[142:143], v[40:41], v[10:11] op_sel_hi:[0,1,1]
	v_pk_fma_f32 v[12:13], v[142:143], v[44:45], v[12:13] op_sel_hi:[0,1,1]
	v_pk_fma_f32 v[14:15], v[142:143], v[48:49], v[14:15] op_sel_hi:[0,1,1]
	v_pk_fma_f32 v[16:17], v[142:143], v[52:53], v[16:17] op_sel_hi:[0,1,1]
	v_pk_fma_f32 v[18:19], v[142:143], v[56:57], v[18:19] op_sel_hi:[0,1,1]
	v_pk_fma_f32 v[20:21], v[142:143], v[60:61], v[20:21] op_sel_hi:[0,1,1]
	v_pk_fma_f32 v[22:23], v[142:143], v[64:65], v[22:23] op_sel_hi:[0,1,1]
	v_pk_fma_f32 v[24:25], v[142:143], v[68:69], v[24:25] op_sel_hi:[0,1,1]
	v_fmac_f32_e32 v2, v142, v75
	v_add_u32_e32 v37, s14, v35
	ds_read2st64_b64 v[38:41], v37 offset1:8
	ds_read2st64_b64 v[42:45], v37 offset0:16 offset1:24
	ds_read2st64_b64 v[46:49], v37 offset0:32 offset1:40
	ds_read2st64_b64 v[50:53], v37 offset0:48 offset1:56
	ds_read2st64_b64 v[54:57], v37 offset0:64 offset1:72
	ds_read2st64_b64 v[58:61], v37 offset0:80 offset1:88
	ds_read2st64_b64 v[62:65], v37 offset0:96 offset1:104
	ds_read2st64_b64 v[66:69], v37 offset0:112 offset1:120
	v_add_u32_e32 v37, 0x10000, v37
	ds_read_b64 v[74:75], v37
	s_waitcnt lgkmcnt(8)
	v_mov_b32_e32 v76, v38
	v_mov_b32_e32 v77, v40
	s_waitcnt lgkmcnt(7)
	v_mov_b32_e32 v78, v42
	v_mov_b32_e32 v79, v44
	s_waitcnt lgkmcnt(6)
	v_mov_b32_e32 v80, v46
	v_mov_b32_e32 v81, v48
	s_waitcnt lgkmcnt(5)
	v_mov_b32_e32 v82, v50
	v_mov_b32_e32 v83, v52
	s_waitcnt lgkmcnt(4)
	v_mov_b32_e32 v84, v54
	v_mov_b32_e32 v85, v56
	s_waitcnt lgkmcnt(3)
	v_mov_b32_e32 v86, v58
	v_mov_b32_e32 v87, v60
	s_waitcnt lgkmcnt(2)
	v_mov_b32_e32 v88, v62
	v_mov_b32_e32 v89, v64
	s_waitcnt lgkmcnt(1)
	v_mov_b32_e32 v90, v66
	v_mov_b32_e32 v91, v68
	s_add_i32 s14, s14, 8
	v_mov_b32_e32 v40, v39
	v_mov_b32_e32 v44, v43
	v_mov_b32_e32 v48, v47
	v_mov_b32_e32 v52, v51
	v_mov_b32_e32 v56, v55
	v_mov_b32_e32 v60, v59
	v_mov_b32_e32 v64, v63
	v_mov_b32_e32 v68, v67
	s_cmpk_eq_i32 s14, 0x200
	s_waitcnt vmcnt(9)
	v_pk_fma_f32 v[10:11], v[144:145], v[76:77], v[10:11] op_sel_hi:[0,1,1]
	v_pk_fma_f32 v[12:13], v[144:145], v[78:79], v[12:13] op_sel_hi:[0,1,1]
	v_pk_fma_f32 v[14:15], v[144:145], v[80:81], v[14:15] op_sel_hi:[0,1,1]
	v_pk_fma_f32 v[16:17], v[144:145], v[82:83], v[16:17] op_sel_hi:[0,1,1]
	v_pk_fma_f32 v[18:19], v[144:145], v[84:85], v[18:19] op_sel_hi:[0,1,1]
	v_pk_fma_f32 v[20:21], v[144:145], v[86:87], v[20:21] op_sel_hi:[0,1,1]
	v_pk_fma_f32 v[22:23], v[144:145], v[88:89], v[22:23] op_sel_hi:[0,1,1]
	v_pk_fma_f32 v[24:25], v[144:145], v[90:91], v[24:25] op_sel_hi:[0,1,1]
	s_waitcnt lgkmcnt(0)
	v_fmac_f32_e32 v2, v144, v74
	s_waitcnt vmcnt(8)
	v_pk_fma_f32 v[10:11], v[146:147], v[40:41], v[10:11] op_sel_hi:[0,1,1]
	v_pk_fma_f32 v[12:13], v[146:147], v[44:45], v[12:13] op_sel_hi:[0,1,1]
	v_pk_fma_f32 v[14:15], v[146:147], v[48:49], v[14:15] op_sel_hi:[0,1,1]
	v_pk_fma_f32 v[16:17], v[146:147], v[52:53], v[16:17] op_sel_hi:[0,1,1]
	v_pk_fma_f32 v[18:19], v[146:147], v[56:57], v[18:19] op_sel_hi:[0,1,1]
	v_pk_fma_f32 v[20:21], v[146:147], v[60:61], v[20:21] op_sel_hi:[0,1,1]
	v_pk_fma_f32 v[22:23], v[146:147], v[64:65], v[22:23] op_sel_hi:[0,1,1]
	v_pk_fma_f32 v[24:25], v[146:147], v[68:69], v[24:25] op_sel_hi:[0,1,1]
	v_fmac_f32_e32 v2, v146, v75
	v_add_u32_e32 v37, s14, v35
	ds_read2st64_b64 v[38:41], v37 offset1:8
	ds_read2st64_b64 v[42:45], v37 offset0:16 offset1:24
	ds_read2st64_b64 v[46:49], v37 offset0:32 offset1:40
	ds_read2st64_b64 v[50:53], v37 offset0:48 offset1:56
	ds_read2st64_b64 v[54:57], v37 offset0:64 offset1:72
	ds_read2st64_b64 v[58:61], v37 offset0:80 offset1:88
	ds_read2st64_b64 v[62:65], v37 offset0:96 offset1:104
	ds_read2st64_b64 v[66:69], v37 offset0:112 offset1:120
	v_add_u32_e32 v37, 0x10000, v37
	ds_read_b64 v[74:75], v37
	s_waitcnt lgkmcnt(8)
	v_mov_b32_e32 v76, v38
	v_mov_b32_e32 v77, v40
	s_waitcnt lgkmcnt(7)
	v_mov_b32_e32 v78, v42
	v_mov_b32_e32 v79, v44
	s_waitcnt lgkmcnt(6)
	v_mov_b32_e32 v80, v46
	v_mov_b32_e32 v81, v48
	s_waitcnt lgkmcnt(5)
	v_mov_b32_e32 v82, v50
	v_mov_b32_e32 v83, v52
	s_waitcnt lgkmcnt(4)
	v_mov_b32_e32 v84, v54
	v_mov_b32_e32 v85, v56
	s_waitcnt lgkmcnt(3)
	v_mov_b32_e32 v86, v58
	v_mov_b32_e32 v87, v60
	s_waitcnt lgkmcnt(2)
	v_mov_b32_e32 v88, v62
	v_mov_b32_e32 v89, v64
	s_waitcnt lgkmcnt(1)
	v_mov_b32_e32 v90, v66
	v_mov_b32_e32 v91, v68
	s_add_i32 s14, s14, 8
	v_mov_b32_e32 v40, v39
	v_mov_b32_e32 v44, v43
	v_mov_b32_e32 v48, v47
	v_mov_b32_e32 v52, v51
	v_mov_b32_e32 v56, v55
	v_mov_b32_e32 v60, v59
	v_mov_b32_e32 v64, v63
	v_mov_b32_e32 v68, v67
	s_cmpk_eq_i32 s14, 0x200
	s_waitcnt vmcnt(7)
	v_pk_fma_f32 v[10:11], v[148:149], v[76:77], v[10:11] op_sel_hi:[0,1,1]
	v_pk_fma_f32 v[12:13], v[148:149], v[78:79], v[12:13] op_sel_hi:[0,1,1]
	v_pk_fma_f32 v[14:15], v[148:149], v[80:81], v[14:15] op_sel_hi:[0,1,1]
	v_pk_fma_f32 v[16:17], v[148:149], v[82:83], v[16:17] op_sel_hi:[0,1,1]
	v_pk_fma_f32 v[18:19], v[148:149], v[84:85], v[18:19] op_sel_hi:[0,1,1]
	v_pk_fma_f32 v[20:21], v[148:149], v[86:87], v[20:21] op_sel_hi:[0,1,1]
	v_pk_fma_f32 v[22:23], v[148:149], v[88:89], v[22:23] op_sel_hi:[0,1,1]
	v_pk_fma_f32 v[24:25], v[148:149], v[90:91], v[24:25] op_sel_hi:[0,1,1]
	s_waitcnt lgkmcnt(0)
	v_fmac_f32_e32 v2, v148, v74
	s_waitcnt vmcnt(6)
; DEVI void ph_setup(const int wv, const Params& p, unsigned char* lds) {
;     ...
;             const float* w = p.in[6] + (size_t)l * 1024 * 6144 + n0 + n;
;             for (int k = kg * 128; k < kg * 128 + 128; ++k) { const float wv = w[(size_t)k * 6144];
; #pragma unroll
;                 for (int r = 0; r < 17; ++r) acc[r] += scv[r * 1024 + k] * wv; }
	v_pk_fma_f32 v[10:11], v[150:151], v[40:41], v[10:11] op_sel_hi:[0,1,1]
	v_pk_fma_f32 v[12:13], v[150:151], v[44:45], v[12:13] op_sel_hi:[0,1,1]
	v_pk_fma_f32 v[14:15], v[150:151], v[48:49], v[14:15] op_sel_hi:[0,1,1]
	v_pk_fma_f32 v[16:17], v[150:151], v[52:53], v[16:17] op_sel_hi:[0,1,1]
	v_pk_fma_f32 v[18:19], v[150:151], v[56:57], v[18:19] op_sel_hi:[0,1,1]
	v_pk_fma_f32 v[20:21], v[150:151], v[60:61], v[20:21] op_sel_hi:[0,1,1]
	v_pk_fma_f32 v[22:23], v[150:151], v[64:65], v[22:23] op_sel_hi:[0,1,1]
	v_pk_fma_f32 v[24:25], v[150:151], v[68:69], v[24:25] op_sel_hi:[0,1,1]
	v_fmac_f32_e32 v2, v150, v75
	v_add_u32_e32 v37, s14, v35
	ds_read2st64_b64 v[38:41], v37 offset1:8
	ds_read2st64_b64 v[42:45], v37 offset0:16 offset1:24
	ds_read2st64_b64 v[46:49], v37 offset0:32 offset1:40
	ds_read2st64_b64 v[50:53], v37 offset0:48 offset1:56
	ds_read2st64_b64 v[54:57], v37 offset0:64 offset1:72
	ds_read2st64_b64 v[58:61], v37 offset0:80 offset1:88
	ds_read2st64_b64 v[62:65], v37 offset0:96 offset1:104
	ds_read2st64_b64 v[66:69], v37 offset0:112 offset1:120
	v_add_u32_e32 v37, 0x10000, v37
	ds_read_b64 v[74:75], v37
	s_waitcnt lgkmcnt(8)
	v_mov_b32_e32 v76, v38
	v_mov_b32_e32 v77, v40
	s_waitcnt lgkmcnt(7)
	v_mov_b32_e32 v78, v42
	v_mov_b32_e32 v79, v44
	s_waitcnt lgkmcnt(6)
	v_mov_b32_e32 v80, v46
	v_mov_b32_e32 v81, v48
	s_waitcnt lgkmcnt(5)
	v_mov_b32_e32 v82, v50
	v_mov_b32_e32 v83, v52
	s_waitcnt lgkmcnt(4)
	v_mov_b32_e32 v84, v54
	v_mov_b32_e32 v85, v56
	s_waitcnt lgkmcnt(3)
	v_mov_b32_e32 v86, v58
	v_mov_b32_e32 v87, v60
	s_waitcnt lgkmcnt(2)
	v_mov_b32_e32 v88, v62
	v_mov_b32_e32 v89, v64
	s_waitcnt lgkmcnt(1)
	v_mov_b32_e32 v90, v66
	v_mov_b32_e32 v91, v68
	s_add_i32 s14, s14, 8
	v_mov_b32_e32 v40, v39
	v_mov_b32_e32 v44, v43
	v_mov_b32_e32 v48, v47
	v_mov_b32_e32 v52, v51
	v_mov_b32_e32 v56, v55
	v_mov_b32_e32 v60, v59
	v_mov_b32_e32 v64, v63
	v_mov_b32_e32 v68, v67
	s_cmpk_eq_i32 s14, 0x200
	s_waitcnt vmcnt(5)
	v_pk_fma_f32 v[10:11], v[152:153], v[76:77], v[10:11] op_sel_hi:[0,1,1]
	v_pk_fma_f32 v[12:13], v[152:153], v[78:79], v[12:13] op_sel_hi:[0,1,1]
	v_pk_fma_f32 v[14:15], v[152:153], v[80:81], v[14:15] op_sel_hi:[0,1,1]
	v_pk_fma_f32 v[16:17], v[152:153], v[82:83], v[16:17] op_sel_hi:[0,1,1]
	v_pk_fma_f32 v[18:19], v[152:153], v[84:85], v[18:19] op_sel_hi:[0,1,1]
	v_pk_fma_f32 v[20:21], v[152:153], v[86:87], v[20:21] op_sel_hi:[0,1,1]
	v_pk_fma_f32 v[22:23], v[152:153], v[88:89], v[22:23] op_sel_hi:[0,1,1]
	v_pk_fma_f32 v[24:25], v[152:153], v[90:91], v[24:25] op_sel_hi:[0,1,1]
	s_waitcnt lgkmcnt(0)
	v_fmac_f32_e32 v2, v152, v74
	s_waitcnt vmcnt(4)
	v_pk_fma_f32 v[10:11], v[154:155], v[40:41], v[10:11] op_sel_hi:[0,1,1]
	v_pk_fma_f32 v[12:13], v[154:155], v[44:45], v[12:13] op_sel_hi:[0,1,1]
	v_pk_fma_f32 v[14:15], v[154:155], v[48:49], v[14:15] op_sel_hi:[0,1,1]
	v_pk_fma_f32 v[16:17], v[154:155], v[52:53], v[16:17] op_sel_hi:[0,1,1]
	v_pk_fma_f32 v[18:19], v[154:155], v[56:57], v[18:19] op_sel_hi:[0,1,1]
	v_pk_fma_f32 v[20:21], v[154:155], v[60:61], v[20:21] op_sel_hi:[0,1,1]
	v_pk_fma_f32 v[22:23], v[154:155], v[64:65], v[22:23] op_sel_hi:[0,1,1]
	v_pk_fma_f32 v[24:25], v[154:155], v[68:69], v[24:25] op_sel_hi:[0,1,1]
	v_fmac_f32_e32 v2, v154, v75
	v_add_u32_e32 v37, s14, v35
	ds_read2st64_b64 v[38:41], v37 offset1:8
	ds_read2st64_b64 v[42:45], v37 offset0:16 offset1:24
	ds_read2st64_b64 v[46:49], v37 offset0:32 offset1:40
	ds_read2st64_b64 v[50:53], v37 offset0:48 offset1:56
	ds_read2st64_b64 v[54:57], v37 offset0:64 offset1:72
	ds_read2st64_b64 v[58:61], v37 offset0:80 offset1:88
	ds_read2st64_b64 v[62:65], v37 offset0:96 offset1:104
	ds_read2st64_b64 v[66:69], v37 offset0:112 offset1:120
	v_add_u32_e32 v37, 0x10000, v37
	ds_read_b64 v[74:75], v37
	s_waitcnt lgkmcnt(8)
	v_mov_b32_e32 v76, v38
	v_mov_b32_e32 v77, v40
	s_waitcnt lgkmcnt(7)
	v_mov_b32_e32 v78, v42
	v_mov_b32_e32 v79, v44
	s_waitcnt lgkmcnt(6)
	v_mov_b32_e32 v80, v46
	v_mov_b32_e32 v81, v48
	s_waitcnt lgkmcnt(5)
	v_mov_b32_e32 v82, v50
	v_mov_b32_e32 v83, v52
	s_waitcnt lgkmcnt(4)
	v_mov_b32_e32 v84, v54
	v_mov_b32_e32 v85, v56
	s_waitcnt lgkmcnt(3)
	v_mov_b32_e32 v86, v58
	v_mov_b32_e32 v87, v60
	s_waitcnt lgkmcnt(2)
	v_mov_b32_e32 v88, v62
	v_mov_b32_e32 v89, v64
	s_waitcnt lgkmcnt(1)
	v_mov_b32_e32 v90, v66
	v_mov_b32_e32 v91, v68
	s_add_i32 s14, s14, 8
	v_mov_b32_e32 v40, v39
	v_mov_b32_e32 v44, v43
	v_mov_b32_e32 v48, v47
	v_mov_b32_e32 v52, v51
	v_mov_b32_e32 v56, v55
	v_mov_b32_e32 v60, v59
	v_mov_b32_e32 v64, v63
	v_mov_b32_e32 v68, v67
	s_cmpk_eq_i32 s14, 0x200
	s_waitcnt vmcnt(3)
	v_pk_fma_f32 v[10:11], v[156:157], v[76:77], v[10:11] op_sel_hi:[0,1,1]
	v_pk_fma_f32 v[12:13], v[156:157], v[78:79], v[12:13] op_sel_hi:[0,1,1]
	v_pk_fma_f32 v[14:15], v[156:157], v[80:81], v[14:15] op_sel_hi:[0,1,1]
	v_pk_fma_f32 v[16:17], v[156:157], v[82:83], v[16:17] op_sel_hi:[0,1,1]
	v_pk_fma_f32 v[18:19], v[156:157], v[84:85], v[18:19] op_sel_hi:[0,1,1]
	v_pk_fma_f32 v[20:21], v[156:157], v[86:87], v[20:21] op_sel_hi:[0,1,1]
	v_pk_fma_f32 v[22:23], v[156:157], v[88:89], v[22:23] op_sel_hi:[0,1,1]
	v_pk_fma_f32 v[24:25], v[156:157], v[90:91], v[24:25] op_sel_hi:[0,1,1]
	s_waitcnt lgkmcnt(0)
; DEVI void ph_setup(const int wv, const Params& p, unsigned char* lds) {
;     ...
;             const float* w = p.in[6] + (size_t)l * 1024 * 6144 + n0 + n;
;             for (int k = kg * 128; k < kg * 128 + 128; ++k) { const float wv = w[(size_t)k * 6144];
; #pragma unroll
;                 for (int r = 0; r < 17; ++r) acc[r] += scv[r * 1024 + k] * wv; }
; #pragma unroll
;             for (int r = 0; r < 17; ++r) red[(kg * 17 + r) * 64 + n] = acc[r];
;             __syncthreads();
;             float* mod = (float*)(p.ws + OFF_MOD);
;             for (int e = tid; e < 17 * 64; e += NTHREADS) { const int r = e >> 6, nn = e & 63; float s = 0.f;
; #pragma unroll
;                 for (int q = 0; q < 8; ++q) s += red[(q * 17 + r) * 64 + nn];
;                 mod[(size_t)(l * 17 + r) * 6144 + n0 + nn] = s + p.in[7][l * 6144 + n0 + nn]; }
	v_fmac_f32_e32 v2, v156, v74
	s_waitcnt vmcnt(2)
	v_pk_fma_f32 v[10:11], v[158:159], v[40:41], v[10:11] op_sel_hi:[0,1,1]
	v_pk_fma_f32 v[12:13], v[158:159], v[44:45], v[12:13] op_sel_hi:[0,1,1]
	v_pk_fma_f32 v[14:15], v[158:159], v[48:49], v[14:15] op_sel_hi:[0,1,1]
	v_pk_fma_f32 v[16:17], v[158:159], v[52:53], v[16:17] op_sel_hi:[0,1,1]
	v_pk_fma_f32 v[18:19], v[158:159], v[56:57], v[18:19] op_sel_hi:[0,1,1]
	v_pk_fma_f32 v[20:21], v[158:159], v[60:61], v[20:21] op_sel_hi:[0,1,1]
	v_pk_fma_f32 v[22:23], v[158:159], v[64:65], v[22:23] op_sel_hi:[0,1,1]
	v_pk_fma_f32 v[24:25], v[158:159], v[68:69], v[24:25] op_sel_hi:[0,1,1]
	v_fmac_f32_e32 v2, v158, v75
	v_add_u32_e32 v37, s14, v35
	ds_read2st64_b64 v[38:41], v37 offset1:8
	ds_read2st64_b64 v[42:45], v37 offset0:16 offset1:24
	ds_read2st64_b64 v[46:49], v37 offset0:32 offset1:40
	ds_read2st64_b64 v[50:53], v37 offset0:48 offset1:56
	ds_read2st64_b64 v[54:57], v37 offset0:64 offset1:72
	ds_read2st64_b64 v[58:61], v37 offset0:80 offset1:88
	ds_read2st64_b64 v[62:65], v37 offset0:96 offset1:104
	ds_read2st64_b64 v[66:69], v37 offset0:112 offset1:120
	v_add_u32_e32 v37, 0x10000, v37
	ds_read_b64 v[74:75], v37
	s_waitcnt lgkmcnt(8)
	v_mov_b32_e32 v76, v38
	v_mov_b32_e32 v77, v40
	s_waitcnt lgkmcnt(7)
	v_mov_b32_e32 v78, v42
	v_mov_b32_e32 v79, v44
	s_waitcnt lgkmcnt(6)
	v_mov_b32_e32 v80, v46
	v_mov_b32_e32 v81, v48
	s_waitcnt lgkmcnt(5)
	v_mov_b32_e32 v82, v50
	v_mov_b32_e32 v83, v52
	s_waitcnt lgkmcnt(4)
	v_mov_b32_e32 v84, v54
	v_mov_b32_e32 v85, v56
	s_waitcnt lgkmcnt(3)
	v_mov_b32_e32 v86, v58
	v_mov_b32_e32 v87, v60
	s_waitcnt lgkmcnt(2)
	v_mov_b32_e32 v88, v62
	v_mov_b32_e32 v89, v64
	s_waitcnt lgkmcnt(1)
	v_mov_b32_e32 v90, v66
	v_mov_b32_e32 v91, v68
	s_add_i32 s14, s14, 8
	v_mov_b32_e32 v40, v39
	v_mov_b32_e32 v44, v43
	v_mov_b32_e32 v48, v47
	v_mov_b32_e32 v52, v51
	v_mov_b32_e32 v56, v55
	v_mov_b32_e32 v60, v59
	v_mov_b32_e32 v64, v63
	v_mov_b32_e32 v68, v67
	s_cmpk_eq_i32 s14, 0x200
	s_waitcnt vmcnt(1)
	v_pk_fma_f32 v[10:11], v[160:161], v[76:77], v[10:11] op_sel_hi:[0,1,1]
	v_pk_fma_f32 v[12:13], v[160:161], v[78:79], v[12:13] op_sel_hi:[0,1,1]
	v_pk_fma_f32 v[14:15], v[160:161], v[80:81], v[14:15] op_sel_hi:[0,1,1]
	v_pk_fma_f32 v[16:17], v[160:161], v[82:83], v[16:17] op_sel_hi:[0,1,1]
	v_pk_fma_f32 v[18:19], v[160:161], v[84:85], v[18:19] op_sel_hi:[0,1,1]
	v_pk_fma_f32 v[20:21], v[160:161], v[86:87], v[20:21] op_sel_hi:[0,1,1]
	v_pk_fma_f32 v[22:23], v[160:161], v[88:89], v[22:23] op_sel_hi:[0,1,1]
	v_pk_fma_f32 v[24:25], v[160:161], v[90:91], v[24:25] op_sel_hi:[0,1,1]
	s_waitcnt lgkmcnt(0)
	v_fmac_f32_e32 v2, v160, v74
	s_waitcnt vmcnt(0)
	v_pk_fma_f32 v[10:11], v[162:163], v[40:41], v[10:11] op_sel_hi:[0,1,1]
	v_pk_fma_f32 v[12:13], v[162:163], v[44:45], v[12:13] op_sel_hi:[0,1,1]
	v_pk_fma_f32 v[14:15], v[162:163], v[48:49], v[14:15] op_sel_hi:[0,1,1]
	v_pk_fma_f32 v[16:17], v[162:163], v[52:53], v[16:17] op_sel_hi:[0,1,1]
	v_pk_fma_f32 v[18:19], v[162:163], v[56:57], v[18:19] op_sel_hi:[0,1,1]
	v_pk_fma_f32 v[20:21], v[162:163], v[60:61], v[20:21] op_sel_hi:[0,1,1]
	v_pk_fma_f32 v[22:23], v[162:163], v[64:65], v[22:23] op_sel_hi:[0,1,1]
	v_pk_fma_f32 v[24:25], v[162:163], v[68:69], v[24:25] op_sel_hi:[0,1,1]
	v_fmac_f32_e32 v2, v162, v75
	s_cbranch_scc0 .LBB0_45
	ds_write2st64_b32 v36, v10, v11 offset1:1
	ds_write2st64_b32 v36, v12, v13 offset0:2 offset1:3
	ds_write2st64_b32 v36, v14, v15 offset0:4 offset1:5
	ds_write2st64_b32 v36, v16, v17 offset0:6 offset1:7
	ds_write2st64_b32 v36, v18, v19 offset0:8 offset1:9
	ds_write2st64_b32 v36, v20, v21 offset0:10 offset1:11
	ds_write2st64_b32 v36, v22, v23 offset0:12 offset1:13
	ds_write2st64_b32 v36, v24, v25 offset0:14 offset1:15
	ds_write_b32 v36, v2 offset:4096
	s_waitcnt lgkmcnt(0)
	s_barrier
	s_and_saveexec_b64 s[14:15], s[2:3]
	s_cbranch_execz .LBB0_23
	s_mul_i32 s17, s16, 0x1800
	s_add_i32 s17, s17, s12
	v_or_b32_e32 v8, s17, v30
	v_readlane_b32 s60, v250, 9
	v_ashrrev_i32_e32 v9, 31, v8
	v_readlane_b32 s74, v250, 23
	v_readlane_b32 s75, v250, 24
	s_mul_i32 s16, s16, 17
	v_lshl_add_u64 v[10:11], s[12:13], 2, v[4:5]
	v_lshl_add_u64 v[8:9], v[8:9], 2, s[74:75]
	s_mov_b64 s[12:13], 0
	v_mov_b32_e32 v2, v0
	v_readlane_b32 s61, v250, 10
	v_readlane_b32 s62, v250, 11
	v_readlane_b32 s63, v250, 12
	v_readlane_b32 s64, v250, 13
	v_readlane_b32 s65, v250, 14
	v_readlane_b32 s66, v250, 15
	v_readlane_b32 s67, v250, 16
	v_readlane_b32 s68, v250, 17
	v_readlane_b32 s69, v250, 18
	v_readlane_b32 s70, v250, 19
	v_readlane_b32 s71, v250, 20
	v_readlane_b32 s72, v250, 21
	v_readlane_b32 s73, v250, 22

; DEVI void ph_convert(const int wv, const Params& p, int l, unsigned char* lds, int mode  , int blk_lo) {
;     ...
;             for (int j = 0; j < 128; ++j) { const float wv = ps[j] * wpo[(size_t)j * 1024];
; #pragma unroll
;                 for (int ii = 0; ii < 16; ++ii) acc[ii] += pw[ii * 128 + j] * wv; }
.LBB0_56:
	v_lshl_add_u64 v[36:37], v[26:27], 0, s[40:41]
	s_add_u32 s44, s42, s40
	global_load_dword v6, v[22:23], off offset:-4096
	global_load_dwordx2 v[38:39], v[36:37], off
	global_load_dwordx2 v[40:41], v[36:37], off offset:512
	global_load_dwordx2 v[42:43], v[36:37], off offset:1024
	global_load_dwordx2 v[44:45], v[36:37], off offset:1536
	global_load_dwordx2 v[46:47], v[36:37], off offset:2048
	global_load_dwordx2 v[48:49], v[36:37], off offset:2560
	global_load_dwordx2 v[50:51], v[36:37], off offset:3072
	global_load_dwordx2 v[52:53], v[36:37], off offset:3584
	v_add_co_u32_e32 v36, vcc, s57, v36
	s_addc_u32 s45, s43, s41
	s_nop 0
	v_addc_co_u32_e32 v37, vcc, 0, v37, vcc
	global_load_dwordx2 v[54:55], v7, s[44:45] offset:-4
	global_load_dwordx2 v[56:57], v[36:37], off
	global_load_dwordx2 v[58:59], v[36:37], off offset:512
	global_load_dwordx2 v[60:61], v[36:37], off offset:1024
	global_load_dwordx2 v[62:63], v[36:37], off offset:1536
	global_load_dwordx2 v[64:65], v[36:37], off offset:2048
	global_load_dwordx2 v[66:67], v[36:37], off offset:2560
	global_load_dwordx2 v[68:69], v[36:37], off offset:3072
	s_nop 0
	global_load_dwordx2 v[36:37], v[36:37], off offset:3584
	s_nop 0
	global_load_dword v35, v[22:23], off
	s_add_u32 s40, s40, 8
	s_addc_u32 s41, s41, 0
	v_lshl_add_u64 v[22:23], v[22:23], 0, s[38:39]
	s_cmpk_eq_i32 s40, 0x200
	v_lshl_add_u64 v[80:81], v[26:27], 0, s[40:41]
	s_add_u32 s44, s42, s40
	global_load_dword v210, v[22:23], off offset:-4096
	global_load_dwordx2 v[82:83], v[80:81], off
	global_load_dwordx2 v[84:85], v[80:81], off offset:512
	global_load_dwordx2 v[86:87], v[80:81], off offset:1024
	global_load_dwordx2 v[88:89], v[80:81], off offset:1536
	global_load_dwordx2 v[90:91], v[80:81], off offset:2048
	global_load_dwordx2 v[92:93], v[80:81], off offset:2560
	global_load_dwordx2 v[94:95], v[80:81], off offset:3072
	global_load_dwordx2 v[96:97], v[80:81], off offset:3584
	v_add_co_u32_e32 v80, vcc, s57, v80
	s_addc_u32 s45, s43, s41
	s_nop 0
	v_addc_co_u32_e32 v81, vcc, 0, v81, vcc
	global_load_dwordx2 v[98:99], v7, s[44:45] offset:-4
	global_load_dwordx2 v[100:101], v[80:81], off
	global_load_dwordx2 v[102:103], v[80:81], off offset:512
	global_load_dwordx2 v[104:105], v[80:81], off offset:1024
	global_load_dwordx2 v[106:107], v[80:81], off offset:1536
	global_load_dwordx2 v[108:109], v[80:81], off offset:2048
	global_load_dwordx2 v[110:111], v[80:81], off offset:2560
	global_load_dwordx2 v[112:113], v[80:81], off offset:3072
	s_nop 0
	global_load_dwordx2 v[80:81], v[80:81], off offset:3584
	s_nop 0
	global_load_dword v79, v[22:23], off
	s_add_u32 s40, s40, 8
	s_addc_u32 s41, s41, 0
	v_lshl_add_u64 v[22:23], v[22:23], 0, s[38:39]
	s_cmpk_eq_i32 s40, 0x200
	s_waitcnt vmcnt(36)
	v_mov_b32_e32 v70, v38
	s_waitcnt vmcnt(35)
	v_mov_b32_e32 v71, v40
	s_waitcnt vmcnt(34)
	v_mov_b32_e32 v72, v42
	s_waitcnt vmcnt(33)
	v_mov_b32_e32 v73, v44
	s_waitcnt vmcnt(32)
	v_mov_b32_e32 v74, v46
	s_waitcnt vmcnt(31)
	v_mov_b32_e32 v75, v48
	s_waitcnt vmcnt(30)
	v_mov_b32_e32 v76, v50
	s_waitcnt vmcnt(29)
	v_mov_b32_e32 v77, v52
	v_mov_b32_e32 v40, v39
	v_mov_b32_e32 v44, v43
	v_mov_b32_e32 v48, v47
	v_mov_b32_e32 v52, v51
	s_waitcnt vmcnt(28)
	v_mul_f32_e32 v6, v54, v6
	s_waitcnt vmcnt(27)
	v_mov_b32_e32 v38, v56
	s_waitcnt vmcnt(26)
	v_mov_b32_e32 v39, v58
	s_waitcnt vmcnt(25)
	v_mov_b32_e32 v42, v60
	s_waitcnt vmcnt(24)
	v_mov_b32_e32 v43, v62
	s_waitcnt vmcnt(23)
	v_mov_b32_e32 v46, v64
	s_waitcnt vmcnt(22)
	v_mov_b32_e32 v47, v66
	s_waitcnt vmcnt(21)
	v_mov_b32_e32 v50, v68
	s_waitcnt vmcnt(20)
	v_mov_b32_e32 v51, v36
	s_waitcnt vmcnt(19)
; DEVI unsigned cvt_pk_bf16(float lo, float hi) { unsigned r; asm volatile("v_cvt_pk_bf16_f32 %0, %1, %2" : "=v"(r) : "v"(lo), "v"(hi)); return r; }
; DEVI void ph_convert(const int wv, const Params& p, int l, unsigned char* lds, int mode  , int blk_lo) {
;     ...
;             for (int j = 0; j < 128; ++j) { const float wv = ps[j] * wpo[(size_t)j * 1024];
; #pragma unroll
;                 for (int ii = 0; ii < 16; ++ii) acc[ii] += pw[ii * 128 + j] * wv; }
;             bf16_t* dst = WB + W_BR + 512 * 1024 + (size_t)(n0 + n) * 512 + g * 128 + ig * 16;
;             u32x4 w0, w1;
;             w0.x = cvt_pk_bf16(acc[0], acc[1]); w0.y = cvt_pk_bf16(acc[2], acc[3]); w0.z = cvt_pk_bf16(acc[4], acc[5]); w0.w = cvt_pk_bf16(acc[6], acc[7]);
;             w1.x = cvt_pk_bf16(acc[8], acc[9]); w1.y = cvt_pk_bf16(acc[10], acc[11]); w1.z = cvt_pk_bf16(acc[12], acc[13]); w1.w = cvt_pk_bf16(acc[14], acc[15]);
;             *(u32x4*)dst = w0; *(u32x4*)(dst + 8) = w1;
	v_mul_f32_e32 v54, v55, v35
	v_mov_b32_e32 v58, v57
	v_mov_b32_e32 v62, v61
	v_mov_b32_e32 v66, v65
	v_mov_b32_e32 v36, v69
	v_pk_fma_f32 v[32:33], v[6:7], v[70:71], v[32:33] op_sel_hi:[0,1,1]
	v_pk_fma_f32 v[30:31], v[6:7], v[72:73], v[30:31] op_sel_hi:[0,1,1]
	v_pk_fma_f32 v[28:29], v[6:7], v[74:75], v[28:29] op_sel_hi:[0,1,1]
	v_pk_fma_f32 v[24:25], v[6:7], v[76:77], v[24:25] op_sel_hi:[0,1,1]
	v_pk_fma_f32 v[20:21], v[6:7], v[38:39], v[20:21] op_sel_hi:[0,1,1]
	v_pk_fma_f32 v[18:19], v[6:7], v[42:43], v[18:19] op_sel_hi:[0,1,1]
	v_pk_fma_f32 v[16:17], v[6:7], v[46:47], v[16:17] op_sel_hi:[0,1,1]
	v_pk_fma_f32 v[14:15], v[6:7], v[50:51], v[14:15] op_sel_hi:[0,1,1]
	v_pk_fma_f32 v[32:33], v[54:55], v[40:41], v[32:33] op_sel_hi:[0,1,1]
	v_pk_fma_f32 v[30:31], v[54:55], v[44:45], v[30:31] op_sel_hi:[0,1,1]
	v_pk_fma_f32 v[28:29], v[54:55], v[48:49], v[28:29] op_sel_hi:[0,1,1]
	v_pk_fma_f32 v[24:25], v[54:55], v[52:53], v[24:25] op_sel_hi:[0,1,1]
	v_pk_fma_f32 v[20:21], v[54:55], v[58:59], v[20:21] op_sel_hi:[0,1,1]
	v_pk_fma_f32 v[18:19], v[54:55], v[62:63], v[18:19] op_sel_hi:[0,1,1]
	v_pk_fma_f32 v[16:17], v[54:55], v[66:67], v[16:17] op_sel_hi:[0,1,1]
	v_pk_fma_f32 v[14:15], v[54:55], v[36:37], v[14:15] op_sel_hi:[0,1,1]
	s_waitcnt vmcnt(17)
	v_mov_b32_e32 v114, v82
	s_waitcnt vmcnt(16)
	v_mov_b32_e32 v115, v84
	s_waitcnt vmcnt(15)
	v_mov_b32_e32 v116, v86
	s_waitcnt vmcnt(14)
	v_mov_b32_e32 v117, v88
	s_waitcnt vmcnt(13)
	v_mov_b32_e32 v118, v90
	s_waitcnt vmcnt(12)
	v_mov_b32_e32 v119, v92
	s_waitcnt vmcnt(11)
	v_mov_b32_e32 v120, v94
	s_waitcnt vmcnt(10)
	v_mov_b32_e32 v121, v96
	v_mov_b32_e32 v84, v83
	v_mov_b32_e32 v88, v87
	v_mov_b32_e32 v92, v91
	v_mov_b32_e32 v96, v95
	s_waitcnt vmcnt(9)
	v_mul_f32_e32 v210, v98, v210
	s_waitcnt vmcnt(8)
	v_mov_b32_e32 v82, v100
	s_waitcnt vmcnt(7)
	v_mov_b32_e32 v83, v102
	s_waitcnt vmcnt(6)
	v_mov_b32_e32 v86, v104
	s_waitcnt vmcnt(5)
	v_mov_b32_e32 v87, v106
	s_waitcnt vmcnt(4)
	v_mov_b32_e32 v90, v108
	s_waitcnt vmcnt(3)
	v_mov_b32_e32 v91, v110
	s_waitcnt vmcnt(2)
	v_mov_b32_e32 v94, v112
	s_waitcnt vmcnt(1)
	v_mov_b32_e32 v95, v80
	s_waitcnt vmcnt(0)
	v_mul_f32_e32 v98, v99, v79
	v_mov_b32_e32 v102, v101
	v_mov_b32_e32 v106, v105
	v_mov_b32_e32 v110, v109
	v_mov_b32_e32 v80, v113
	v_pk_fma_f32 v[32:33], v[210:211], v[114:115], v[32:33] op_sel_hi:[0,1,1]
	v_pk_fma_f32 v[30:31], v[210:211], v[116:117], v[30:31] op_sel_hi:[0,1,1]
	v_pk_fma_f32 v[28:29], v[210:211], v[118:119], v[28:29] op_sel_hi:[0,1,1]
	v_pk_fma_f32 v[24:25], v[210:211], v[120:121], v[24:25] op_sel_hi:[0,1,1]
	v_pk_fma_f32 v[20:21], v[210:211], v[82:83], v[20:21] op_sel_hi:[0,1,1]
	v_pk_fma_f32 v[18:19], v[210:211], v[86:87], v[18:19] op_sel_hi:[0,1,1]
	v_pk_fma_f32 v[16:17], v[210:211], v[90:91], v[16:17] op_sel_hi:[0,1,1]
	v_pk_fma_f32 v[14:15], v[210:211], v[94:95], v[14:15] op_sel_hi:[0,1,1]
	v_pk_fma_f32 v[32:33], v[98:99], v[84:85], v[32:33] op_sel_hi:[0,1,1]
	v_pk_fma_f32 v[30:31], v[98:99], v[88:89], v[30:31] op_sel_hi:[0,1,1]
	v_pk_fma_f32 v[28:29], v[98:99], v[92:93], v[28:29] op_sel_hi:[0,1,1]
	v_pk_fma_f32 v[24:25], v[98:99], v[96:97], v[24:25] op_sel_hi:[0,1,1]
	v_pk_fma_f32 v[20:21], v[98:99], v[102:103], v[20:21] op_sel_hi:[0,1,1]
	v_pk_fma_f32 v[18:19], v[98:99], v[106:107], v[18:19] op_sel_hi:[0,1,1]
	v_pk_fma_f32 v[16:17], v[98:99], v[110:111], v[16:17] op_sel_hi:[0,1,1]
	v_pk_fma_f32 v[14:15], v[98:99], v[80:81], v[14:15] op_sel_hi:[0,1,1]
	s_cbranch_scc0 .LBB0_56
	s_lshl_b32 s40, s46, 6
	s_and_b32 s40, s40, 0x3c0
	v_or_b32_e32 v6, s40, v2
	v_lshlrev_b32_e32 v6, 10, v6
	v_lshl_add_u64 v[22:23], s[10:11], 0, v[6:7]
	v_lshl_add_u64 v[22:23], s[36:37], 1, v[22:23]
	v_lshl_add_u64 v[36:37], v[4:5], 1, v[22:23]
	v_cvt_pk_bf16_f32 v26, v32, v33
	v_cvt_pk_bf16_f32 v27, v30, v31
	v_cvt_pk_bf16_f32 v28, v28, v29
	v_cvt_pk_bf16_f32 v29, v24, v25
	v_cvt_pk_bf16_f32 v20, v20, v21
	v_cvt_pk_bf16_f32 v21, v18, v19
	v_cvt_pk_bf16_f32 v22, v16, v17
	v_cvt_pk_bf16_f32 v23, v14, v15
	global_store_dwordx4 v[36:37], v[26:29], off
	global_store_dwordx4 v[36:37], v[20:23], off offset:16
	s_branch .LBB0_52
